# v9 + static s_setprio 1 for waves 4-7 during the SSD scan phase
# baseline (speedup 1.0000x reference)
; #define LAS __attribute__((address_space(3)))
; __device__ __forceinline__ int opaque_tid() { int t = threadIdx.x; asm volatile("" : "+v"(t)); return t; }
; template <bool DRY>
; __device__ __forceinline__ void phase_ssd_scan(const Args& a, int j, unsigned char* lds_raw) {
;     LAS unsigned char* L = (LAS unsigned char*)lds_raw;
;     bf16_t* BIG = (bf16_t*)(a.ws + WS_BIG); const float* DT = (const float*)(a.ws + WS_DT); float* SSQY = (float*)(a.ws + WS_SSQ128);
;     const float* A_log = a.in[9] + j * 32; const float* Dp = a.in[10] + j * 32;
;     const int tid = opaque_tid(), lane = tid & 63, wave = __builtin_amdgcn_readfirstlane(tid >> 6);
;     const int role = (wave == 1) ? 6 : ((wave == 6) ? 1 : wave);
;     const int c16 = lane & 15, q4 = lane >> 4, li = role >> 1, pi = role & 1;
;     for (int it = blockIdx.x; it < 256; it += gridDim.x) {
;         const int xc = it & 7, slot = it >> 3, pair = xc + 8 * (slot >> 3), sub = slot & 7;
;         SsdItem I; I.b = pair >> 3; I.g = pair & 7; I.h = I.g * 4 + (sub >> 1); I.ph = sub & 1;
;         I.Ah = -__expf(A_log[I.h]); I.Dh = Dp[I.h];
; #pragma unroll
;         for (int i = 0; i < 2; ++i) { I.offB[i] = (unsigned)(lane * BIGW + 4096 + I.g * 128 + (wave + 8 * i) * 8) * 2u; const int id = tid + 512 * i; I.offC[i] = (unsigned)((id >> 4) * BIGW + 5120 + I.g * 128 + (id & 15) * 8) * 2u; }
;         I.offX = (unsigned)(lane * BIGW + DI_ + I.h * 64 + I.ph * 32 + wave * 8) * 2u;
;         I.offZ = (unsigned)((16 * li + c16) * BIGW + I.h * 64 + I.ph * 32 + 16 * pi + 4 * q4) * 2u;
;         I.offDT = (unsigned)(lane * 32 + I.h) * 4u;
.LBB0_705:
	s_cmp_lt_i32 s74, 2
	s_mov_b64 s[0:1], -1
	s_cbranch_scc1 .LBB0_752
	s_cmp_eq_u32 s74, 2
	s_cbranch_scc0 .LBB0_751
	v_readlane_b32 s0, v253, 63
	s_waitcnt vmcnt(0) lgkmcnt(0)
	v_mov_b32_e32 v2, v0
	v_readlane_b32 s1, v254, 0
	s_andn2_b64 vcc, exec, s[0:1]
	v_readfirstlane_b32 s0, v2
	s_cbranch_vccnz .LBB0_751
	v_readfirstlane_b32 s100, v0
	s_nop 3
	s_lshr_b32 s100, s100, 6
	s_cmp_lt_u32 s100, 4
	s_cbranch_scc1 .Lsp_lo
	s_setprio 1
.Lsp_lo:
	v_writelane_b32 v255, s74, 31
	v_writelane_b32 v255, s69, 32
	s_mov_b32 s2, s22
	v_writelane_b32 v255, s2, 12
	v_and_b32_e32 v5, 63, v2
	v_mov_b32_e32 v1, 0x1000
	v_writelane_b32 v255, s3, 13
	s_lshl_b32 s2, s22, 5
	s_ashr_i32 s3, s2, 31
	s_lshl_b64 s[2:3], s[2:3], 2
	s_waitcnt lgkmcnt(0)
	s_add_u32 s4, s54, s2
	s_addc_u32 s5, s55, s3
	s_add_u32 s2, s56, s2
	s_addc_u32 s3, s57, s3
	s_ashr_i32 s0, s0, 6
	s_cmp_lg_u32 s0, 6
	v_writelane_b32 v255, s4, 10
	s_cselect_b32 s1, s0, 1
	s_cmp_lg_u32 s0, 1
	v_writelane_b32 v255, s5, 11
	s_cselect_b32 s1, s1, 6
	v_writelane_b32 v255, s2, 22
	s_and_b32 s19, s1, 1
	s_ashr_i32 s1, s1, 1
	v_writelane_b32 v255, s3, 23
	s_lshl_b32 s36, s0, 4
	s_lshl_b32 s2, s19, 5
	s_cmp_lt_i32 s0, 4
	s_cselect_b64 s[4:5], -1, 0
	s_movk_i32 s22, 0x1800
	v_writelane_b32 v255, s4, 20
	s_cmp_gt_i32 s0, 3
	v_mad_u32_u24 v4, v5, s22, v1
	v_writelane_b32 v255, s5, 21
	s_cselect_b64 s[4:5], -1, 0
	v_bfe_u32 v10, v2, 4, 2
	v_lshl_add_u32 v1, s0, 3, v4
	v_writelane_b32 v255, s4, 24
	s_lshl_b32 s3, s0, 9
	s_lshl_b32 s0, s0, 5
	v_readlane_b32 s18, v254, 51
	v_lshlrev_b32_e32 v15, 3, v10
	v_writelane_b32 v255, s5, 25
	s_add_i32 s3, s3, 0
	s_add_i32 s4, s18, s0
	s_add_i32 s3, s3, 0x16800
	v_add_u32_e32 v19, s4, v15
	s_add_i32 s20, s36, 0
	s_add_i32 s4, s2, 0
	s_lshl_b32 s14, s19, 1
	v_and_b32_e32 v11, 15, v2
	v_mul_u32_u24_e32 v12, 0x1800, v5
	s_cmp_le_i32 s14, s1
	v_add3_u32 v108, v4, v12, s36
	v_lshl_or_b32 v4, s1, 4, v11
	v_add_u32_e32 v20, s4, v15
	s_movk_i32 s4, 0x90
	s_cselect_b64 s[88:89], -1, 0
	s_cmp_eq_u32 s14, s1
	v_mul_lo_u32 v32, v4, s4
	s_cselect_b64 s[4:5], -1, 0
	s_lshl_b32 s68, s19, 6
	s_or_b32 s16, s14, 1
	s_cmp_ge_i32 s14, s1
	s_movk_i32 s24, 0x110
	s_cselect_b64 s[84:85], -1, 0
	s_cmp_eq_u32 s16, s1
	v_lshlrev_b32_e32 v13, 3, v2
	v_mad_u32_u24 v110, v5, s24, 0
	v_ashrrev_i32_e32 v24, 4, v2
	v_add_u32_e32 v26, 0x200, v2
	v_and_b32_e32 v111, 48, v2
	s_cselect_b64 s[14:15], -1, 0
	s_lshl_b32 s69, s16, 5
	v_mov_b32_e32 v36, s18
	s_movk_i32 s18, 0x60
	v_readlane_b32 s25, v254, 52
	v_and_b32_e32 v14, 0x78, v13
	v_lshlrev_b32_e32 v109, 7, v5
	v_lshlrev_b32_e32 v18, 2, v5
	v_lshl_add_u32 v23, v5, 4, v110
	v_ashrrev_i32_e32 v26, 4, v26
	v_mul_u32_u24_e32 v29, 0x60, v5
	v_lshl_or_b32 v33, s19, 7, v111
	s_cmp_eq_u32 s19, 0
	v_writelane_b32 v255, s19, 18
	v_lshl_or_b32 v35, s19, 4, v11
	v_mul_lo_u32 v37, v4, s18
	v_cmp_gt_u32_e64 s[18:19], 16, v5
	v_mov_b32_e32 v5, s25
	v_mul_lo_u32 v114, v24, s22
	v_lshlrev_b32_e32 v10, 2, v10
	v_mad_u32_u24 v36, v35, s24, v36
	v_mad_u32_u24 v35, v35, s24, v5
	v_mul_lo_u32 v115, v26, s22
	v_or_b32_e32 v5, v114, v14
	v_bfe_u32 v17, v2, 2, 2
	v_and_b32_e32 v13, 24, v13
	v_cmp_gt_u32_e64 s[6:7], v10, v11
	v_cmp_lt_u32_e64 s[8:9], v10, v11
	v_or_b32_e32 v34, 2, v10
	v_or_b32_e32 v10, 3, v10
	v_add_u32_e32 v118, 0x1400, v5
	v_or_b32_e32 v5, v115, v14
	s_mul_i32 s1, s1, 0x30000
	s_movk_i32 s23, 0x3000
	v_or_b32_e32 v17, v15, v17
	v_add_u32_e32 v13, 0, v13
	v_lshlrev_b32_e32 v22, 4, v2
	v_cmp_gt_u32_e64 s[10:11], v34, v11
	v_cmp_gt_u32_e64 s[12:13], v10, v11
	v_lshl_or_b32 v10, s16, 4, v11
	v_lshl_or_b32 v34, s16, 6, v111
	s_movk_i32 s16, 0x120
	v_add_u32_e32 v120, 0x1400, v5
	v_mov_b32_e32 v5, s1
	v_and_b32_e32 v22, 0xf0, v22
	v_mul_u32_u24_e32 v28, 0x60, v17
	v_mul_lo_u32 v30, v4, s24
	v_add_u32_e32 v112, s91, v32
	v_or_b32_e32 v32, s2, v11
	v_mad_u32_u24 v17, v17, s16, v13
	s_cselect_b64 s[16:17], -1, 0
	s_add_i32 s21, s25, s0
	v_mad_u32_u24 v5, v11, s23, v5
	v_mul_lo_u32 v16, v4, s23
	v_mul_u32_u24_e32 v21, 0x110, v11
	v_add_u32_e32 v22, 0, v22
	v_mul_lo_u32 v25, v24, s24
	v_mul_lo_u32 v27, v26, s24
	v_add_u32_e32 v30, 0, v30
	v_lshlrev_b32_e32 v2, 2, v4
	v_add_u32_e32 v31, 0, v111
	v_mul_u32_u24_e32 v32, 0x110, v32
	v_mul_u32_u24_e32 v10, 0x110, v10
	v_add_u32_e32 v38, s21, v15
	s_add_i32 s21, s36, 0x2080
	v_or3_b32 v121, v5, s2, v15
	v_ashrrev_i32_e32 v5, 31, v4
	v_readlane_b32 s80, v253, 61
	s_mov_b32 s26, 0x9300000
	v_add_u32_e32 v113, v112, v15
	v_or3_b32 v116, v16, v15, s2
	v_or_b32_e32 v117, 0x1400, v14
	v_lshl_add_u32 v119, v12, 1, s21
	v_lshlrev_b64 v[74:75], 2, v[4:5]
	v_add_u32_e32 v122, v19, v21
	v_add_u32_e32 v123, v36, v111
	v_add_u32_e32 v124, v38, v21
	v_add_u32_e32 v125, v35, v111
	v_add_u32_e32 v126, s3, v18
	v_add_u32_e32 v127, v22, v25
	v_add_u32_e32 v128, s36, v23
	v_add_u32_e32 v129, v22, v27
	v_add_u32_e32 v130, s20, v29
	v_add_u32_e32 v131, v30, v111
	v_add_u32_e32 v132, s3, v2
	v_add_u32_e32 v133, v31, v32
	v_add_u32_e32 v134, s3, v33
	v_add_u32_e32 v135, v31, v10
	v_add_u32_e32 v136, s3, v34
	v_add_u32_e32 v137, s0, v17
	v_add_u32_e32 v138, v13, v28
	v_add_u32_e32 v139, v20, v37
	s_mov_b32 s72, s92
	s_mov_b32 s73, s92
	v_readlane_b32 s81, v253, 62
	s_branch .LBB0_710

; template <bool DRY>
; __device__ __forceinline__ void phase_ssd_scan(const Args& a, int j, unsigned char* lds_raw) {
;     ...
;         for (int c = 0; c < 64; c += 2) {
;             ssd_chunk<DRY>(R0, st, L, BIG, DT, SSQY, I, c, tid, lane, wave, li, pi, c16, q4);
;             ssd_chunk<DRY>(R1, st, L, BIG, DT, SSQY, I, c + 1, tid, lane, wave, li, pi, c16, q4);
;         }
;     }
; }
.LBB0_750:
	s_setprio 0
	v_readlane_b32 s80, v254, 55
	v_readlane_b32 s88, v254, 57
	v_readlane_b32 s81, v254, 56
	v_readlane_b32 s89, v254, 58
	s_mov_b32 s18, 0x9301000
	s_mov_b32 s26, 0x9300000
	v_readlane_b32 s22, v255, 12
	v_readlane_b32 s69, v255, 32
	v_readlane_b32 s74, v255, 31
	v_readlane_b32 s23, v255, 13
